# loop-edge rotation step 2: next tile's global-load addresses formed before the per-tile barrier, loads issue right after it
# baseline (speedup 1.0000x reference)
; #define MFMA32(a, b, c) __builtin_amdgcn_mfma_f32_32x32x16_bf16((a), (b), (c), 0, 0, 0)
; __device__ __forceinline__ void diff_unit(const Frame& F, int b, int h, int qi, float lam, int dry) {
;     ...
;             float ps = 0.f;
; #pragma unroll
;             for (int r = 0; r < 16; ++r) { s0[r] = __builtin_amdgcn_exp2f(s0[r] * LOG2E - ms); ps += s0[r]; }
;             if (!meta) {
; #pragma unroll
;                 for (int r = 0; r < 16; ++r) { s1[r] = __builtin_amdgcn_exp2f(s1[r] * LOG2E - ms); ps += s1[r]; }
;             }
;             lsum += ps;
;             __builtin_amdgcn_s_setprio(1);
;             { const bf16x8 pf = pack_step(s0, 0);
;               O[0] = MFMA32(vpre0, pf, O[0]); O[1] = MFMA32(vpre1, pf, O[1]); O[2] = MFMA32(vpre2, pf, O[2]); O[3] = MFMA32(vpre3, pf, O[3]); }
.LBB0_295:
	v_sub_f32_e32 v238, 0, v185
	v_sub_f32_e32 v239, 0, v185
	v_sub_f32_e32 v240, 0, v185
	v_sub_f32_e32 v241, 0, v185
	v_sub_f32_e32 v242, 0, v185
	v_sub_f32_e32 v243, 0, v185
	v_sub_f32_e32 v244, 0, v185
	v_sub_f32_e32 v245, 0, v185
	v_sub_f32_e32 v246, 0, v185
	v_sub_f32_e32 v247, 0, v185
	v_sub_f32_e32 v248, 0, v185
	v_sub_f32_e32 v249, 0, v185
	v_sub_f32_e32 v250, 0, v185
	v_sub_f32_e32 v251, 0, v185
	v_sub_f32_e32 v252, 0, v185
	v_sub_f32_e32 v253, 0, v185
	v_sub_f32_e32 v16, v16, v185
	v_exp_f32_e32 v16, v16
	v_sub_f32_e32 v17, v17, v185
	v_exp_f32_e32 v17, v17
	v_sub_f32_e32 v18, v18, v185
	v_exp_f32_e32 v18, v18
	v_sub_f32_e32 v19, v19, v185
	v_exp_f32_e32 v19, v19
	v_sub_f32_e32 v20, v20, v185
	v_add_f32_e32 v24, 0, v16
	v_exp_f32_e32 v20, v20
	v_sub_f32_e32 v21, v21, v185
	v_add_f32_e32 v24, v17, v24
	v_exp_f32_e32 v21, v21
	v_sub_f32_e32 v22, v22, v185
	v_add_f32_e32 v24, v18, v24
	v_exp_f32_e32 v22, v22
	v_sub_f32_e32 v23, v23, v185
	v_add_f32_e32 v24, v19, v24
	v_exp_f32_e32 v23, v23
	v_sub_f32_e32 v25, 0xff800000, v185
	v_add_f32_e32 v24, v20, v24
	v_exp_f32_e32 v25, v25
	v_add_f32_e32 v24, v21, v24
	v_add_f32_e32 v24, v22, v24
	v_add_f32_e32 v24, v23, v24
	v_add_f32_e32 v24, v25, v24
	v_add_f32_e32 v24, v25, v24
	v_add_f32_e32 v24, v25, v24
	v_add_f32_e32 v24, v25, v24
	s_mov_b64 s[2:3], 0x10000
	v_add_f32_e32 v24, v25, v24
	v_lshl_add_u64 v[200:201], v[188:189], 0, s[2:3]
	v_lshl_add_u64 v[202:203], v[190:191], 0, s[2:3]
	s_mov_b64 s[2:3], 0x8000
	s_lshl_b32 s1, s33, 1
	v_add_f32_e32 v24, v25, v24
	v_lshl_add_u64 v[192:193], v[188:189], 0, s[2:3]
	v_lshl_add_u64 v[196:197], v[190:191], 0, s[2:3]
	s_and_b32 s2, s1, 0x700
	s_and_b32 s1, s82, 15
	v_add_f32_e32 v24, v25, v24
	s_mov_b64 s[4:5], 0x18000
	v_lshl_add_u32 v153, s1, 7, v217
	s_lshl_b32 s1, s1, 18
	s_lshl_b32 s95, s90, 1
	v_add_f32_e32 v24, v25, v24
	v_mov_b32_e32 v2, v1
	v_mov_b32_e32 v3, v1
	v_mov_b32_e32 v4, v1
	v_mov_b32_e32 v5, v1
	v_mov_b32_e32 v6, v1
	v_mov_b32_e32 v7, v1
	v_mov_b32_e32 v8, v1
	v_mov_b32_e32 v9, v1
	v_mov_b32_e32 v10, v1
	v_mov_b32_e32 v11, v1
	v_mov_b32_e32 v12, v1
	v_mov_b32_e32 v13, v1
	v_mov_b32_e32 v14, v1
	v_mov_b32_e32 v15, v1
	s_mul_hi_i32 s73, s0, 0x1010
	s_mul_i32 s72, s0, 0x1010
	v_lshl_add_u64 v[194:195], v[188:189], 0, s[4:5]
	v_lshl_add_u64 v[198:199], v[190:191], 0, s[4:5]
	s_add_u32 s89, s1, 0x40000
	s_add_i32 s95, s95, 3
	s_or_b32 s10, s70, 1
	s_addk_i32 s70, 0x5f
	v_add_f32_e32 v158, v1, v24
	s_setprio 1
	v_cvt_pk_bf16_f32 v76, v16, v17
	v_cvt_pk_bf16_f32 v77, v18, v19
	v_cvt_pk_bf16_f32 v78, v20, v21
	v_cvt_pk_bf16_f32 v79, v22, v23
	s_nop 1
	v_mfma_f32_32x32x16_bf16 v[48:63], v[32:35], v[76:79], v[0:15]
	v_mfma_f32_32x32x16_bf16 v[32:47], v[64:67], v[76:79], v[0:15]
	v_mfma_f32_32x32x16_bf16 v[16:31], v[72:75], v[76:79], v[0:15]
	v_mfma_f32_32x32x16_bf16 v[0:15], v[68:71], v[76:79], v[0:15]
	s_setprio 0
	s_mul_hi_i32 s1, s0, 0x808000
	s_mul_i32 s0, s0, 0x808000
	s_or_b32 s0, s0, s2
	v_lshl_add_u64 v[186:187], v[182:183], 0, s[0:1]
	s_mov_b32 s71, 2
	s_mov_b64 s[64:65], 0
	s_mov_b32 s91, 64
	s_waitcnt vmcnt(3)
	ds_write_b128 v209, v[112:115] offset:17408
	s_waitcnt vmcnt(2)
	ds_write_b128 v209, v[116:119] offset:26112
	s_waitcnt vmcnt(1)
	ds_write_b128 v210, v[120:123] offset:55296
	s_waitcnt vmcnt(0)
	ds_write_b128 v211, v[124:127] offset:30720
	v_add_u32_e32 v223, 0x4400, v212
	v_add_u32_e32 v222, 0x5000, v213
	s_add_u32 s0, s64, 0x6d28000
	s_addc_u32 s1, s65, 0
	v_lshl_add_u64 v[66:67], v[186:187], 0, s[0:1]
	s_add_u32 s0, s64, 0x6d38000
	s_addc_u32 s1, s65, 0
	v_lshl_add_u64 v[68:69], v[186:187], 0, s[0:1]
	s_add_u32 s0, s64, 0xae28000
	s_addc_u32 s1, s65, 0
	v_lshl_add_u64 v[64:65], v[186:187], 0, s[0:1]
	s_add_u32 s0, s64, 0xae38000
	s_addc_u32 s1, s65, 0
	v_lshl_add_u64 v[70:71], v[186:187], 0, s[0:1]
	s_waitcnt lgkmcnt(0)
	s_barrier
	s_branch .LBB0_297
.LBB0_296:
	s_add_i32 s71, s71, 1
	s_add_i32 s0, s71, -1
	s_and_b32 s0, s0, 1
	s_mul_i32 s1, s0, 0x5000
	s_mulk_i32 s0, 0x4400
	v_add_u32_e32 v223, s0, v212
	v_add_u32_e32 v222, s1, v213
	s_add_u32 s64, s64, 0x20000
	s_addc_u32 s65, s65, 0
	s_add_u32 s0, s64, 0x6d28000
	s_addc_u32 s1, s65, 0
	v_lshl_add_u64 v[66:67], v[186:187], 0, s[0:1]
	s_add_u32 s0, s64, 0x6d38000
	s_addc_u32 s1, s65, 0
	v_lshl_add_u64 v[68:69], v[186:187], 0, s[0:1]
	s_add_u32 s0, s64, 0xae28000
	s_addc_u32 s1, s65, 0
	v_lshl_add_u64 v[64:65], v[186:187], 0, s[0:1]
	s_add_u32 s0, s64, 0xae38000
	s_addc_u32 s1, s65, 0
	v_lshl_add_u64 v[70:71], v[186:187], 0, s[0:1]
	s_add_i32 s91, s91, 64
	s_cmp_eq_u32 s89, s64
	v_subrev_u32_e32 v153, 64, v153
	s_waitcnt lgkmcnt(0)
	s_barrier
	s_cbranch_scc1 .LBB0_307

; #define D_LOAD(key0) do { st0 = *(const u32x4*)(kg + (size_t)(key0) * 1024); st1 = *(const u32x4*)(kg + (size_t)((key0) + 32) * 1024); st2 = *(const u32x4*)(vg + (size_t)(key0) * 1024); st3 = *(const u32x4*)(vg + (size_t)((key0) + 32) * 1024); } while (0)
; __device__ __forceinline__ void diff_unit(const Frame& F, int b, int h, int qi, float lam, int dry) {
;     ...
;         if (it + 1 < nt) D_LOAD(NMETA + 64 * it);
;         const bool meta = (it == 0);
;         if (meta || key0 <= tqw + 31) {
.LBB0_300:
	global_load_dwordx4 v[112:115], v[66:67], off
	global_load_dwordx4 v[116:119], v[68:69], off
	global_load_dwordx4 v[120:123], v[64:65], off
	global_load_dwordx4 v[124:127], v[70:71], off
	s_cmp_gt_u32 s91, s70
	s_cbranch_scc1 .LBB0_299

; #define MFMA32(a, b, c) __builtin_amdgcn_mfma_f32_32x32x16_bf16((a), (b), (c), 0, 0, 0)
; __device__ __forceinline__ void diff_unit(const Frame& F, int b, int h, int qi, float lam, int dry) {
;     ...
;             float ps = 0.f;
; #pragma unroll
;             for (int r = 0; r < 16; ++r) { s0[r] = __builtin_amdgcn_exp2f(s0[r] * LOG2E - ms); ps += s0[r]; }
;             if (!meta) {
; #pragma unroll
;                 for (int r = 0; r < 16; ++r) { s1[r] = __builtin_amdgcn_exp2f(s1[r] * LOG2E - ms); ps += s1[r]; }
;             }
;             lsum += ps;
;             __builtin_amdgcn_s_setprio(1);
;             { const bf16x8 pf = pack_step(s0, 0);
;               O[0] = MFMA32(vpre0, pf, O[0]); O[1] = MFMA32(vpre1, pf, O[1]); O[2] = MFMA32(vpre2, pf, O[2]); O[3] = MFMA32(vpre3, pf, O[3]); }
.LBB0_314:
	v_sub_f32_e32 v238, 0, v158
	v_sub_f32_e32 v239, 0, v158
	v_sub_f32_e32 v240, 0, v158
	v_sub_f32_e32 v241, 0, v158
	v_sub_f32_e32 v242, 0, v158
	v_sub_f32_e32 v243, 0, v158
	v_sub_f32_e32 v244, 0, v158
	v_sub_f32_e32 v245, 0, v158
	v_sub_f32_e32 v246, 0, v158
	v_sub_f32_e32 v247, 0, v158
	v_sub_f32_e32 v248, 0, v158
	v_sub_f32_e32 v249, 0, v158
	v_sub_f32_e32 v250, 0, v158
	v_sub_f32_e32 v251, 0, v158
	v_sub_f32_e32 v252, 0, v158
	v_sub_f32_e32 v253, 0, v158
	v_sub_f32_e32 v16, v16, v158
	v_exp_f32_e32 v16, v16
	v_sub_f32_e32 v17, v17, v158
	v_exp_f32_e32 v17, v17
	v_sub_f32_e32 v18, v18, v158
	v_exp_f32_e32 v18, v18
	v_sub_f32_e32 v19, v19, v158
	v_exp_f32_e32 v19, v19
	v_sub_f32_e32 v20, v20, v158
	v_add_f32_e32 v24, 0, v16
	v_exp_f32_e32 v20, v20
	v_sub_f32_e32 v21, v21, v158
	v_add_f32_e32 v24, v17, v24
	v_exp_f32_e32 v21, v21
	v_sub_f32_e32 v22, v22, v158
	v_add_f32_e32 v24, v18, v24
	v_exp_f32_e32 v22, v22
	v_sub_f32_e32 v23, v23, v158
	v_add_f32_e32 v24, v19, v24
	v_exp_f32_e32 v23, v23
	v_sub_f32_e32 v25, 0xff800000, v158
	v_add_f32_e32 v24, v20, v24
	v_exp_f32_e32 v25, v25
	v_add_f32_e32 v24, v21, v24
	v_add_f32_e32 v24, v22, v24
	v_add_f32_e32 v24, v23, v24
	v_add_f32_e32 v24, v25, v24
	v_add_f32_e32 v24, v25, v24
	v_add_f32_e32 v24, v25, v24
	v_add_f32_e32 v24, v25, v24
	v_add_f32_e32 v24, v25, v24
	v_add_f32_e32 v24, v25, v24
	v_add_f32_e32 v24, v25, v24
	s_lshl_b32 s10, s1, 1
	v_add_f32_e32 v24, v25, v24
	v_mov_b32_e32 v2, v1
	v_mov_b32_e32 v3, v1
	v_mov_b32_e32 v4, v1
	v_mov_b32_e32 v5, v1
	v_mov_b32_e32 v6, v1
	v_mov_b32_e32 v7, v1
	v_mov_b32_e32 v8, v1
	v_mov_b32_e32 v9, v1
	v_mov_b32_e32 v10, v1
	v_mov_b32_e32 v11, v1
	v_mov_b32_e32 v12, v1
	v_mov_b32_e32 v13, v1
	v_mov_b32_e32 v14, v1
	v_mov_b32_e32 v15, v1
	s_add_i32 s10, s10, 3
	s_or_b32 s70, s71, 1
	s_addk_i32 s71, 0x5f
	v_add_f32_e32 v153, v1, v24
	s_setprio 1
	v_cvt_pk_bf16_f32 v76, v16, v17
	v_cvt_pk_bf16_f32 v77, v18, v19
	v_cvt_pk_bf16_f32 v78, v20, v21
	v_cvt_pk_bf16_f32 v79, v22, v23
	s_nop 1
	v_mfma_f32_32x32x16_bf16 v[48:63], v[32:35], v[76:79], v[0:15]
	v_mfma_f32_32x32x16_bf16 v[32:47], v[64:67], v[76:79], v[0:15]
	v_mfma_f32_32x32x16_bf16 v[16:31], v[72:75], v[76:79], v[0:15]
	v_mfma_f32_32x32x16_bf16 v[0:15], v[68:71], v[76:79], v[0:15]
	s_setprio 0
	s_lshl_b32 s1, s1, 18
	s_add_u32 s95, s1, 0x40000
	v_add_u32_e32 v185, s0, v217
	s_mov_b32 s2, 2
	s_mov_b64 s[66:67], 0
	s_mov_b32 s3, 64
	s_waitcnt vmcnt(3)
	ds_write_b128 v209, v[112:115] offset:17408
	s_waitcnt vmcnt(2)
	ds_write_b128 v209, v[116:119] offset:26112
	s_waitcnt vmcnt(1)
	ds_write_b128 v210, v[120:123] offset:55296
	s_waitcnt vmcnt(0)
	ds_write_b128 v211, v[124:127] offset:30720
	v_add_u32_e32 v189, 0x4400, v212
	v_add_u32_e32 v188, 0x5000, v213
	s_add_u32 s0, s66, 0x6d28000
	s_addc_u32 s1, s67, 0
	v_lshl_add_u64 v[66:67], v[186:187], 0, s[0:1]
	s_add_u32 s0, s66, 0x6d38000
	s_addc_u32 s1, s67, 0
	v_lshl_add_u64 v[68:69], v[186:187], 0, s[0:1]
	s_add_u32 s0, s66, 0xae28000
	s_addc_u32 s1, s67, 0
	v_lshl_add_u64 v[64:65], v[186:187], 0, s[0:1]
	s_add_u32 s0, s66, 0xae38000
	s_addc_u32 s1, s67, 0
	v_lshl_add_u64 v[70:71], v[186:187], 0, s[0:1]
	s_waitcnt lgkmcnt(0)
	s_barrier
	s_branch .LBB0_316
.LBB0_315:
	s_add_i32 s2, s2, 1
	s_add_i32 s0, s2, -1
	s_and_b32 s0, s0, 1
	s_mul_i32 s1, s0, 0x5000
	s_mulk_i32 s0, 0x4400
	v_add_u32_e32 v189, s0, v212
	v_add_u32_e32 v188, s1, v213
	s_add_u32 s66, s66, 0x20000
	s_addc_u32 s67, s67, 0
	s_add_u32 s0, s66, 0x6d28000
	s_addc_u32 s1, s67, 0
	v_lshl_add_u64 v[66:67], v[186:187], 0, s[0:1]
	s_add_u32 s0, s66, 0x6d38000
	s_addc_u32 s1, s67, 0
	v_lshl_add_u64 v[68:69], v[186:187], 0, s[0:1]
	s_add_u32 s0, s66, 0xae28000
	s_addc_u32 s1, s67, 0
	v_lshl_add_u64 v[64:65], v[186:187], 0, s[0:1]
	s_add_u32 s0, s66, 0xae38000
	s_addc_u32 s1, s67, 0
	v_lshl_add_u64 v[70:71], v[186:187], 0, s[0:1]
	s_add_i32 s3, s3, 64
	s_cmp_eq_u32 s95, s66
	v_subrev_u32_e32 v185, 64, v185
	s_waitcnt lgkmcnt(0)
	s_barrier
	s_cbranch_scc1 .LBB0_326

; #define D_LOAD(key0) do { st0 = *(const u32x4*)(kg + (size_t)(key0) * 1024); st1 = *(const u32x4*)(kg + (size_t)((key0) + 32) * 1024); st2 = *(const u32x4*)(vg + (size_t)(key0) * 1024); st3 = *(const u32x4*)(vg + (size_t)((key0) + 32) * 1024); } while (0)
; __device__ __forceinline__ void diff_unit(const Frame& F, int b, int h, int qi, float lam, int dry) {
;     ...
;         if (it + 1 < nt) D_LOAD(NMETA + 64 * it);
;         const bool meta = (it == 0);
;         if (meta || key0 <= tqw + 31) {
.LBB0_319:
	global_load_dwordx4 v[112:115], v[66:67], off
	global_load_dwordx4 v[116:119], v[68:69], off
	global_load_dwordx4 v[120:123], v[64:65], off
	global_load_dwordx4 v[124:127], v[70:71], off
	s_cmp_gt_u32 s3, s71
	s_cbranch_scc1 .LBB0_318
